# attention: the older wave's post-QK priority drop moved below the four LDS fragment reads that follow the QK chain
# baseline (speedup 1.0000x reference)
.Lattn_ld:
	global_load_dwordx4 v[164:167], v[190:191], off
	global_load_dwordx4 v[148:151], v[190:191], off offset:64
	global_load_dwordx4 v[152:155], v[190:191], off offset:128
	global_load_dwordx4 v[172:175], v[190:191], off offset:192
	global_load_dwordx4 v[156:159], v[242:243], off
	global_load_dwordx4 v[160:163], v[242:243], off offset:64
	v_add_co_u32_e32 v190, vcc, s79, v252
	s_nop 1
	v_addc_co_u32_e32 v191, vcc, 0, v253, vcc
	global_load_dwordx4 v[144:147], v[252:253], off
	global_load_dwordx4 v[168:171], v[190:191], off
	v_add_co_u32_e32 v190, vcc, 0x100000, v252
	s_nop 1
	v_addc_co_u32_e32 v191, vcc, 0, v253, vcc
	v_add_co_u32_e32 v242, vcc, 0x180000, v252
	s_nop 1
	v_addc_co_u32_e32 v243, vcc, 0, v253, vcc
	global_load_dwordx4 v[176:179], v[190:191], off
	global_load_dwordx4 v[180:183], v[242:243], off
	s_cmp_le_i32 s15, s17
	s_cbranch_scc0 .LBB0_57
	s_setprio 1
	s_waitcnt lgkmcnt(7)
	v_mfma_f32_32x32x16_bf16 v[80:95], v[244:247], v[96:99], 0
	ds_read_b128 v[244:247], v220 offset:256
	s_waitcnt lgkmcnt(7)
	v_mfma_f32_32x32x16_bf16 v[80:95], v[248:251], v[100:103], v[80:95]
	ds_read_b128 v[248:251], v220 offset:288
	s_waitcnt lgkmcnt(7)
	v_mfma_f32_32x32x16_bf16 v[80:95], v[222:225], v[104:107], v[80:95]
	ds_read_b128 v[222:225], v220 offset:320
	s_waitcnt lgkmcnt(7)
	v_mfma_f32_32x32x16_bf16 v[80:95], v[230:233], v[108:111], v[80:95]
	ds_read_b128 v[230:233], v220 offset:352
	s_waitcnt lgkmcnt(7)
	v_mfma_f32_32x32x16_bf16 v[80:95], v[64:67], v[112:115], v[80:95]
	s_waitcnt lgkmcnt(6)
	v_mfma_f32_32x32x16_bf16 v[80:95], v[68:71], v[116:119], v[80:95]
	s_waitcnt lgkmcnt(5)
	v_mfma_f32_32x32x16_bf16 v[80:95], v[72:75], v[120:123], v[80:95]
	s_waitcnt lgkmcnt(4)
	v_mfma_f32_32x32x16_bf16 v[80:95], v[76:79], v[124:127], v[80:95]
	s_waitcnt lgkmcnt(3)
	v_mfma_f32_32x32x16_bf16 v[80:95], v[244:247], v[128:131], v[80:95]
	ds_read_b128 v[244:247], v220 offset:12800
	s_waitcnt lgkmcnt(3)
	v_mfma_f32_32x32x16_bf16 v[80:95], v[248:251], v[132:135], v[80:95]
	ds_read_b128 v[248:251], v220 offset:12832
	s_waitcnt lgkmcnt(3)
	v_mfma_f32_32x32x16_bf16 v[80:95], v[222:225], v[136:139], v[80:95]
	ds_read_b128 v[222:225], v220 offset:12864
	s_waitcnt lgkmcnt(3)
	v_mfma_f32_32x32x16_bf16 v[80:95], v[230:233], v[140:143], v[80:95]
	ds_read_b128 v[230:233], v220 offset:12896
	s_waitcnt lgkmcnt(3)
	v_mfma_f32_32x32x16_bf16 v[64:79], v[244:247], v[96:99], 0
	ds_read_b128 v[244:247], v220 offset:12928
	s_waitcnt lgkmcnt(3)
	v_mfma_f32_32x32x16_bf16 v[64:79], v[248:251], v[100:103], v[64:79]
	ds_read_b128 v[248:251], v220 offset:12960
	s_waitcnt lgkmcnt(3)
	v_mfma_f32_32x32x16_bf16 v[64:79], v[222:225], v[104:107], v[64:79]
	ds_read_b128 v[222:225], v220 offset:12992
	s_waitcnt lgkmcnt(3)
	v_mfma_f32_32x32x16_bf16 v[64:79], v[230:233], v[108:111], v[64:79]
	ds_read_b128 v[230:233], v220 offset:13024
	s_waitcnt lgkmcnt(3)
	v_mfma_f32_32x32x16_bf16 v[64:79], v[244:247], v[112:115], v[64:79]
	ds_read_b128 v[244:247], v220 offset:13056
	s_waitcnt lgkmcnt(3)
	v_mfma_f32_32x32x16_bf16 v[64:79], v[248:251], v[116:119], v[64:79]
	ds_read_b128 v[248:251], v220 offset:13088
	s_waitcnt lgkmcnt(3)
	v_mfma_f32_32x32x16_bf16 v[64:79], v[222:225], v[120:123], v[64:79]
	ds_read_b128 v[222:225], v220 offset:13120
	s_waitcnt lgkmcnt(3)
	v_mfma_f32_32x32x16_bf16 v[64:79], v[230:233], v[124:127], v[64:79]
	ds_read_b128 v[230:233], v220 offset:13152
	s_waitcnt lgkmcnt(3)
	v_mfma_f32_32x32x16_bf16 v[64:79], v[244:247], v[128:131], v[64:79]
	s_waitcnt lgkmcnt(2)
	v_mfma_f32_32x32x16_bf16 v[64:79], v[248:251], v[132:135], v[64:79]
	s_waitcnt lgkmcnt(1)
	v_mfma_f32_32x32x16_bf16 v[64:79], v[222:225], v[136:139], v[64:79]
	s_waitcnt lgkmcnt(0)
	v_mfma_f32_32x32x16_bf16 v[64:79], v[230:233], v[140:143], v[64:79]
	ds_read_b128 v[244:247], v239 offset:25600
	ds_read_b128 v[248:251], v239 offset:30208
	ds_read_b128 v[222:225], v239 offset:34816
	ds_read_b128 v[230:233], v239 offset:39424
	s_getreg_b32 s4, hwreg(HW_REG_HW_ID, 0, 4)
	s_bitcmp1_b32 s4, 0
	s_cbranch_scc1 .Lprio_keep0
	s_setprio 0
.Lprio_keep0:
	s_add_i32 s4, s15, 63
	s_cmp_gt_i32 s4, s18
	s_cbranch_scc0 .Lattn_nomask
	v_add_u32_e32 v220, s15, v197
	v_cmp_gt_i32_e32 vcc, v220, v214
	s_nop 1
	v_cndmask_b32_e32 v221, v80, v234, vcc
	v_cmp_lt_i32_e32 vcc, v220, v214
	s_nop 1
	v_cndmask_b32_e32 v80, v221, v80, vcc
	v_add_u32_e32 v221, 2, v220
	v_cndmask_b32_e32 v81, v234, v81, vcc
	v_cmp_le_i32_e32 vcc, v221, v214
	v_add_u32_e32 v221, 3, v220
	s_nop 0
	v_cndmask_b32_e32 v82, v234, v82, vcc
	v_cmp_le_i32_e32 vcc, v221, v214
	v_add_u32_e32 v221, 8, v220
	s_nop 0
	v_cndmask_b32_e32 v83, v234, v83, vcc
	v_cmp_le_i32_e32 vcc, v221, v214
	v_add_u32_e32 v221, 9, v220
	s_nop 0
	v_cndmask_b32_e32 v84, v234, v84, vcc
	v_cmp_le_i32_e32 vcc, v221, v214
	v_add_u32_e32 v221, 10, v220
	s_nop 0
	v_cndmask_b32_e32 v85, v234, v85, vcc
	v_cmp_le_i32_e32 vcc, v221, v214
	v_add_u32_e32 v221, 11, v220
	s_nop 0
	v_cndmask_b32_e32 v86, v234, v86, vcc
	v_cmp_le_i32_e32 vcc, v221, v214
	v_add_u32_e32 v221, 16, v220
	s_nop 0
	v_cndmask_b32_e32 v87, v234, v87, vcc
	v_cmp_le_i32_e32 vcc, v221, v214
	v_add_u32_e32 v221, 17, v220
	s_nop 0
	v_cndmask_b32_e32 v88, v234, v88, vcc
	v_cmp_le_i32_e32 vcc, v221, v214
	v_add_u32_e32 v221, 18, v220
	s_nop 0
	v_cndmask_b32_e32 v89, v234, v89, vcc
	v_cmp_le_i32_e32 vcc, v221, v214
	v_add_u32_e32 v221, 19, v220
	s_nop 0
	v_cndmask_b32_e32 v90, v234, v90, vcc
	v_cmp_le_i32_e32 vcc, v221, v214
	v_add_u32_e32 v221, 24, v220
	s_nop 0
	v_cndmask_b32_e32 v91, v234, v91, vcc
	v_cmp_le_i32_e32 vcc, v221, v214
	v_add_u32_e32 v221, 25, v220
	s_nop 0
	v_cndmask_b32_e32 v92, v234, v92, vcc
	v_cmp_le_i32_e32 vcc, v221, v214
	v_add_u32_e32 v221, 26, v220
	s_nop 0
	v_cndmask_b32_e32 v93, v234, v93, vcc
	v_cmp_le_i32_e32 vcc, v221, v214
	v_add_u32_e32 v221, 27, v220
	s_nop 0
	v_cndmask_b32_e32 v94, v234, v94, vcc
	v_cmp_le_i32_e32 vcc, v221, v214
	v_add_u32_e32 v221, 32, v220
	s_nop 0
	v_cndmask_b32_e32 v95, v234, v95, vcc
	v_cmp_le_i32_e32 vcc, v221, v214
	v_add_u32_e32 v221, 33, v220
	s_nop 0
	v_cndmask_b32_e32 v64, v234, v64, vcc
	v_cmp_le_i32_e32 vcc, v221, v214
	v_add_u32_e32 v221, 34, v220
	s_nop 0
	v_cndmask_b32_e32 v65, v234, v65, vcc
	v_cmp_le_i32_e32 vcc, v221, v214
	v_add_u32_e32 v221, 35, v220
	s_nop 0
	v_cndmask_b32_e32 v66, v234, v66, vcc
	v_cmp_le_i32_e32 vcc, v221, v214
	v_add_u32_e32 v221, 40, v220
	s_nop 0
	v_cndmask_b32_e32 v67, v234, v67, vcc
	v_cmp_le_i32_e32 vcc, v221, v214
	v_add_u32_e32 v221, 41, v220
	s_nop 0
	v_cndmask_b32_e32 v68, v234, v68, vcc
	v_cmp_le_i32_e32 vcc, v221, v214
	v_add_u32_e32 v221, 42, v220
	s_nop 0
	v_cndmask_b32_e32 v69, v234, v69, vcc
	v_cmp_le_i32_e32 vcc, v221, v214
	v_add_u32_e32 v221, 43, v220
	s_nop 0
	v_cndmask_b32_e32 v70, v234, v70, vcc
	v_cmp_le_i32_e32 vcc, v221, v214
	v_add_u32_e32 v221, 48, v220
	s_nop 0
	v_cndmask_b32_e32 v71, v234, v71, vcc
	v_cmp_le_i32_e32 vcc, v221, v214
	v_add_u32_e32 v221, 49, v220
	s_nop 0
	v_cndmask_b32_e32 v72, v234, v72, vcc
	v_cmp_le_i32_e32 vcc, v221, v214
	v_add_u32_e32 v221, 50, v220
	s_nop 0
	v_cndmask_b32_e32 v73, v234, v73, vcc
	v_cmp_le_i32_e32 vcc, v221, v214
	v_add_u32_e32 v221, 51, v220
	s_nop 0
	v_cndmask_b32_e32 v74, v234, v74, vcc
	v_cmp_le_i32_e32 vcc, v221, v214
	v_add_u32_e32 v221, 56, v220
	s_nop 0
	v_cndmask_b32_e32 v75, v234, v75, vcc
	v_cmp_le_i32_e32 vcc, v221, v214
	v_add_u32_e32 v221, 57, v220
	s_nop 0
	v_cndmask_b32_e32 v76, v234, v76, vcc
	v_cmp_le_i32_e32 vcc, v221, v214
	v_add_u32_e32 v221, 58, v220
	v_add_u32_e32 v220, 59, v220
	v_cndmask_b32_e32 v77, v234, v77, vcc
	v_cmp_le_i32_e32 vcc, v221, v214
	s_nop 1
	v_cndmask_b32_e32 v78, v234, v78, vcc
	v_cmp_le_i32_e32 vcc, v220, v214
	s_nop 1
	v_cndmask_b32_e32 v79, v234, v79, vcc
